# GEMM K-loop: duplicate s_waitcnt lgkmcnt(0) after the barriers removed (on top of the MFMA-shadow interleave)
# speedup vs baseline: 1.0027x; 1.0027x over previous
; #define LDA(dst, b, h) for (int m = 0; m < 4; ++m) for (int k = 0; k < 2; ++k) \
;     dst[m][k] = *reinterpret_cast<const bf16x8*>(SA(b, h) + lds_byte(wr * 64 + m * 16 + fr, k * 32 + fq * 8))
; #define LDB(dst, b, h) for (int n = 0; n < 2; ++n) for (int k = 0; k < 2; ++k) \
;     dst[n][k] = *reinterpret_cast<const bf16x8*>(SB(b, h) + lds_byte(wc * 32 + n * 16 + fr, k * 32 + fq * 8))
; #define MMA(ai, bj, At_, Bt_) do { __builtin_amdgcn_s_setprio(1); \
;     for (int m = 0; m < 4; ++m) for (int n = 0; n < 2; ++n) for (int k = 0; k < 2; ++k) \
;       acc[ai][bj][m][n] = __builtin_amdgcn_mfma_f32_16x16x32_bf16(Bt_[n][k], At_[m][k], acc[ai][bj][m][n], 0, 0, 0); \
;     __builtin_amdgcn_s_setprio(0); } while (0)
; #define WAIT_V(n) asm volatile("s_waitcnt vmcnt(" #n ")" ::: "memory")
; #define WAIT_L(n) asm volatile("s_waitcnt lgkmcnt(" #n ")" ::: "memory")
; #define BAR __builtin_amdgcn_s_barrier()
; #define SCHED __builtin_amdgcn_sched_barrier(0)
; #define STG(P, PTR, LD, O0) do { const bf16_t* _g = (PTR); \
;     __builtin_amdgcn_global_load_lds((const unsigned*)(_g + O0), (lds_u32*)((P) + swave * 1024), 16, 0, 0); \
;     __builtin_amdgcn_global_load_lds((const unsigned*)(_g + (size_t)64 * (LD) + O0), (lds_u32*)((P) + swave * 1024 + 8192), 16, 0, 0); } while (0)
; #define LDA(dst, b, h) for (int m = 0; m < 4; ++m) for (int k = 0; k < 2; ++k) \
;     dst[m][k] = *reinterpret_cast<const bf16x8*>(SA(b, h) + lds_byte(wr * 64 + m * 16 + fr, k * 32 + fq * 8))
; #define WAIT_V(n) asm volatile("s_waitcnt vmcnt(" #n ")" ::: "memory")
; __device__ __forceinline__ void gemm_stream(int swave, const GemmJob& J, char* shm, int vb, int G) {
;     ...
;     for (int t = 0; t < nt; t += 2) {
;       const bool last = (t == nt - 2);
;       const bf16_t* xA = last ? nA : cA; const bf16_t* xA1 = last ? nA1 : cA1; const int k2 = last ? 0 : t + 2;
;       const bf16_t* b2 = last ? nB : cB + (size_t)(t + 2) * 64; const bf16_t* b3 = b2 + 64;
;       LDB(B0, 0, 0); SCHED; LDA(At, 0, 0); STGA(SA(1, 1), cA, cA1, t + 1, 1);
;       WAIT_L(8); BAR; WAIT_L(0); MMA(0, 0, At, B0); BAR; SCHED;
;       LDB(B1, 0, 1); STG(SB(0, 0), b2, ldb, offB0);
;       BAR; WAIT_L(0); MMA(0, 1, At, B1); BAR;
;       LDA(At, 0, 1); STGA(SA(0, 0), xA, xA1, k2, 0);
;       BAR; WAIT_L(0); MMA(1, 0, At, B0); BAR; SCHED;
;       STG(SB(0, 1), b2 + hB, ldb, offB0);
;       WAIT_V(6); BAR; MMA(1, 1, At, B1); BAR;
.LBB0_729:
	ds_read_b128 v[164:167], v139
	ds_read_b128 v[168:171], v139 offset:1024
	ds_read_b128 v[172:175], v139 offset:2048
	ds_read_b128 v[176:179], v139 offset:3072
	s_cmp_eq_u32 s49, s29
	s_cselect_b64 s[68:69], -1, 0
	s_and_b64 s[64:65], s[68:69], exec
	s_cselect_b32 s52, s10, s8
	s_cselect_b32 s64, s11, s9
	s_add_i32 s33, s2, 2
	s_and_b64 s[68:69], s[68:69], exec
	s_cselect_b32 s71, s15, s21
	s_cselect_b32 s70, s14, s20
	s_cselect_b32 s68, 0, s33
	s_cselect_b32 s65, s12, s16
	s_cselect_b32 s66, s13, s17
	s_or_b32 s2, s2, 1
	s_cmp_lt_u32 s2, s36
	s_cselect_b64 vcc, -1, 0
	s_and_b64 s[2:3], vcc, exec
	s_cselect_b32 s3, 0, s36
	s_cselect_b32 s2, s38, s37
	s_not_b32 s3, s3
	s_add_i32 s94, s3, s29
	s_and_b64 s[72:73], vcc, exec
	s_cselect_b32 s3, s9, s17
	s_cselect_b32 s69, s8, s16
	s_lshl_b64 s[72:73], s[94:95], 7
	s_add_u32 s69, s69, s72
	s_addc_u32 s74, s3, s73
	s_mov_b32 s3, s95
	s_lshl_b64 s[72:73], s[2:3], 8
	s_add_u32 s72, s69, s72
	v_cndmask_b32_e32 v2, v138, v0, vcc
	s_addc_u32 s73, s74, s73
	s_add_i32 m0, s42, 0xc000
	s_lshl_b64 s[2:3], s[2:3], 7
	v_lshlrev_b64 v[212:213], 1, v[2:3]
	s_add_u32 s2, s72, s2
	v_lshl_add_u64 v[214:215], s[72:73], 0, v[212:213]
	s_addc_u32 s3, s73, s3
	ds_read_b128 v[180:183], v144
	ds_read_b128 v[184:187], v144 offset:1024
	ds_read_b128 v[188:191], v145
	ds_read_b128 v[192:195], v145 offset:1024
	ds_read_b128 v[196:199], v159
	ds_read_b128 v[200:203], v159 offset:1024
	ds_read_b128 v[204:207], v160
	ds_read_b128 v[208:211], v160 offset:1024
	global_load_lds_dwordx4 v[214:215], off
	v_lshl_add_u64 v[212:213], s[2:3], 0, v[212:213]
	s_add_i32 m0, s42, 0xe000
	s_nop 0
	global_load_lds_dwordx4 v[212:213], off
	s_waitcnt lgkmcnt(8)
	s_barrier
	s_waitcnt lgkmcnt(0)
	v_mfma_f32_16x16x32_bf16 v[128:131], v[164:167], v[180:183], v[128:131]
	v_mfma_f32_16x16x32_bf16 v[124:127], v[172:175], v[180:183], v[124:127]
	v_mfma_f32_16x16x32_bf16 v[120:123], v[164:167], v[188:191], v[120:123]
	v_mfma_f32_16x16x32_bf16 v[116:119], v[172:175], v[188:191], v[116:119]
	v_mfma_f32_16x16x32_bf16 v[104:107], v[164:167], v[196:199], v[104:107]
	v_mfma_f32_16x16x32_bf16 v[100:103], v[172:175], v[196:199], v[100:103]
	v_mfma_f32_16x16x32_bf16 v[88:91], v[164:167], v[204:207], v[88:91]
	v_mfma_f32_16x16x32_bf16 v[84:87], v[172:175], v[204:207], v[84:87]
	v_mfma_f32_16x16x32_bf16 v[128:131], v[168:171], v[184:187], v[128:131]
	v_mfma_f32_16x16x32_bf16 v[124:127], v[176:179], v[184:187], v[124:127]
	v_mfma_f32_16x16x32_bf16 v[120:123], v[168:171], v[192:195], v[120:123]
	v_mfma_f32_16x16x32_bf16 v[116:119], v[176:179], v[192:195], v[116:119]
	v_mfma_f32_16x16x32_bf16 v[104:107], v[168:171], v[200:203], v[104:107]
	v_mfma_f32_16x16x32_bf16 v[100:103], v[176:179], v[200:203], v[100:103]
	v_mfma_f32_16x16x32_bf16 v[88:91], v[168:171], v[208:211], v[88:91]
	v_mfma_f32_16x16x32_bf16 v[84:87], v[176:179], v[208:211], v[84:87]
	s_barrier
	s_add_u32 s2, s70, s0
	s_mov_b32 m0, s43
	v_lshl_add_u64 v[228:229], s[70:71], 0, v[136:137]
	s_addc_u32 s3, s71, s1
	ds_read_b128 v[212:215], v161
	ds_read_b128 v[216:219], v161 offset:1024
	ds_read_b128 v[220:223], v161 offset:2048
	ds_read_b128 v[224:227], v161 offset:3072
	global_load_lds_dwordx4 v[228:229], off
	v_lshl_add_u64 v[230:231], s[2:3], 0, v[136:137]
	s_mov_b32 m0, s44
	s_nop 0
	global_load_lds_dwordx4 v[230:231], off
	s_barrier
	s_waitcnt lgkmcnt(0)
	v_mfma_f32_16x16x32_bf16 v[112:115], v[212:215], v[180:183], v[112:115]
	v_mfma_f32_16x16x32_bf16 v[108:111], v[220:223], v[180:183], v[108:111]
	s_cmp_lt_u32 s68, s36
	s_cselect_b64 vcc, -1, 0
	v_mfma_f32_16x16x32_bf16 v[96:99], v[212:215], v[188:191], v[96:99]
	s_and_b64 s[70:71], vcc, exec
	s_cselect_b32 s70, s38, s37
	v_mfma_f32_16x16x32_bf16 v[92:95], v[220:223], v[188:191], v[92:95]
	s_sub_i32 s69, s68, s36
	s_min_u32 s94, s68, s69
	v_mfma_f32_16x16x32_bf16 v[80:83], v[212:215], v[196:199], v[80:83]
	s_and_b64 s[72:73], vcc, exec
	s_cselect_b32 s69, s64, s66
	v_mfma_f32_16x16x32_bf16 v[76:79], v[220:223], v[196:199], v[76:79]
	s_cselect_b32 s71, s52, s65
	s_lshl_b64 s[72:73], s[94:95], 7
	v_mfma_f32_16x16x32_bf16 v[72:75], v[212:215], v[204:207], v[72:75]
	v_cndmask_b32_e32 v2, v138, v0, vcc
	s_add_u32 s72, s71, s72
	v_mfma_f32_16x16x32_bf16 v[68:71], v[220:223], v[204:207], v[68:71]
	s_mov_b32 s71, s95
	v_mfma_f32_16x16x32_bf16 v[112:115], v[216:219], v[184:187], v[112:115]
	s_addc_u32 s73, s69, s73
	v_mfma_f32_16x16x32_bf16 v[108:111], v[224:227], v[184:187], v[108:111]
	v_lshlrev_b64 v[232:233], 1, v[2:3]
	v_mfma_f32_16x16x32_bf16 v[96:99], v[216:219], v[192:195], v[96:99]
	s_lshl_b64 s[70:71], s[70:71], 7
	v_mfma_f32_16x16x32_bf16 v[92:95], v[224:227], v[192:195], v[92:95]
	v_lshl_add_u64 v[234:235], s[72:73], 0, v[232:233]
	v_mfma_f32_16x16x32_bf16 v[80:83], v[216:219], v[200:203], v[80:83]
	s_add_u32 s72, s72, s70
	v_mfma_f32_16x16x32_bf16 v[76:79], v[224:227], v[200:203], v[76:79]
	s_mov_b32 m0, s42
	v_mfma_f32_16x16x32_bf16 v[72:75], v[216:219], v[208:211], v[72:75]
	s_addc_u32 s73, s73, s71
	v_mfma_f32_16x16x32_bf16 v[68:71], v[224:227], v[208:211], v[68:71]
	s_barrier
	ds_read_b128 v[180:183], v144 offset:16384
	ds_read_b128 v[184:187], v144 offset:17408
	ds_read_b128 v[188:191], v145 offset:16384
	ds_read_b128 v[192:195], v145 offset:17408
	ds_read_b128 v[196:199], v159 offset:16384
	ds_read_b128 v[200:203], v159 offset:17408
	ds_read_b128 v[204:207], v160 offset:16384
	ds_read_b128 v[208:211], v160 offset:17408
	global_load_lds_dwordx4 v[234:235], off
	v_lshl_add_u64 v[234:235], s[72:73], 0, v[232:233]
	s_mov_b32 m0, s39
	s_nop 0
	global_load_lds_dwordx4 v[234:235], off
	s_barrier
; #define LDA(dst, b, h) for (int m = 0; m < 4; ++m) for (int k = 0; k < 2; ++k) \
;     dst[m][k] = *reinterpret_cast<const bf16x8*>(SA(b, h) + lds_byte(wr * 64 + m * 16 + fr, k * 32 + fq * 8))
; #define LDB(dst, b, h) for (int n = 0; n < 2; ++n) for (int k = 0; k < 2; ++k) \
;     dst[n][k] = *reinterpret_cast<const bf16x8*>(SB(b, h) + lds_byte(wc * 32 + n * 16 + fr, k * 32 + fq * 8))
; #define MMA(ai, bj, At_, Bt_) do { __builtin_amdgcn_s_setprio(1); \
;     for (int m = 0; m < 4; ++m) for (int n = 0; n < 2; ++n) for (int k = 0; k < 2; ++k) \
;       acc[ai][bj][m][n] = __builtin_amdgcn_mfma_f32_16x16x32_bf16(Bt_[n][k], At_[m][k], acc[ai][bj][m][n], 0, 0, 0); \
;     __builtin_amdgcn_s_setprio(0); } while (0)
; #define WAIT_V(n) asm volatile("s_waitcnt vmcnt(" #n ")" ::: "memory")
; #define WAIT_L(n) asm volatile("s_waitcnt lgkmcnt(" #n ")" ::: "memory")
; #define BAR __builtin_amdgcn_s_barrier()
; #define SCHED __builtin_amdgcn_sched_barrier(0)
; #define STG(P, PTR, LD, O0) do { const bf16_t* _g = (PTR); \
;     __builtin_amdgcn_global_load_lds((const unsigned*)(_g + O0), (lds_u32*)((P) + swave * 1024), 16, 0, 0); \
;     __builtin_amdgcn_global_load_lds((const unsigned*)(_g + (size_t)64 * (LD) + O0), (lds_u32*)((P) + swave * 1024 + 8192), 16, 0, 0); } while (0)
; #define LDA(dst, b, h) for (int m = 0; m < 4; ++m) for (int k = 0; k < 2; ++k) \
;     dst[m][k] = *reinterpret_cast<const bf16x8*>(SA(b, h) + lds_byte(wr * 64 + m * 16 + fr, k * 32 + fq * 8))
; #define LDB(dst, b, h) for (int n = 0; n < 2; ++n) for (int k = 0; k < 2; ++k) \
;     dst[n][k] = *reinterpret_cast<const bf16x8*>(SB(b, h) + lds_byte(wc * 32 + n * 16 + fr, k * 32 + fq * 8))
; __device__ __forceinline__ void gemm_stream(int swave, const GemmJob& J, char* shm, int vb, int G) {
;     ...
;       WAIT_L(8); BAR; WAIT_L(0); MMA(0, 0, At, B0); BAR; SCHED;
;       LDB(B1, 0, 1); STG(SB(0, 0), b2, ldb, offB0);
;       BAR; WAIT_L(0); MMA(0, 1, At, B1); BAR;
;       LDA(At, 0, 1); STGA(SA(0, 0), xA, xA1, k2, 0);
;       BAR; WAIT_L(0); MMA(1, 0, At, B0); BAR; SCHED;
;       STG(SB(0, 1), b2 + hB, ldb, offB0);
;       WAIT_V(6); BAR; MMA(1, 1, At, B1); BAR;
;       LDB(B0, 1, 0); SCHED; LDA(At, 1, 0); STGA(SA(0, 1), xA, xA1, k2, 1);
;       WAIT_L(8); BAR; WAIT_L(0); MMA(0, 0, At, B0); BAR; SCHED;
;       LDB(B1, 1, 1); STG(SB(1, 0), b3, ldb, offB0);
;       BAR; WAIT_L(0); MMA(0, 1, At, B1); BAR;
	s_waitcnt lgkmcnt(0)
	v_mfma_f32_16x16x32_bf16 v[64:67], v[164:167], v[180:183], v[64:67]
	v_mfma_f32_16x16x32_bf16 v[60:63], v[172:175], v[180:183], v[60:63]
	v_mfma_f32_16x16x32_bf16 v[56:59], v[164:167], v[188:191], v[56:59]
	v_mfma_f32_16x16x32_bf16 v[52:55], v[172:175], v[188:191], v[52:55]
	v_mfma_f32_16x16x32_bf16 v[40:43], v[164:167], v[196:199], v[40:43]
	v_mfma_f32_16x16x32_bf16 v[36:39], v[172:175], v[196:199], v[36:39]
	v_mfma_f32_16x16x32_bf16 v[24:27], v[164:167], v[204:207], v[24:27]
	v_mfma_f32_16x16x32_bf16 v[20:23], v[172:175], v[204:207], v[20:23]
	v_mfma_f32_16x16x32_bf16 v[64:67], v[168:171], v[184:187], v[64:67]
	v_mfma_f32_16x16x32_bf16 v[60:63], v[176:179], v[184:187], v[60:63]
	v_mfma_f32_16x16x32_bf16 v[56:59], v[168:171], v[192:195], v[56:59]
	v_mfma_f32_16x16x32_bf16 v[52:55], v[176:179], v[192:195], v[52:55]
	v_mfma_f32_16x16x32_bf16 v[40:43], v[168:171], v[200:203], v[40:43]
	v_mfma_f32_16x16x32_bf16 v[36:39], v[176:179], v[200:203], v[36:39]
	v_mfma_f32_16x16x32_bf16 v[24:27], v[168:171], v[208:211], v[24:27]
	v_mfma_f32_16x16x32_bf16 v[20:23], v[176:179], v[208:211], v[20:23]
	s_barrier
	s_add_u32 s2, s2, s0
	s_addc_u32 s3, s3, s1
	v_lshl_add_u64 v[234:235], s[2:3], 0, v[136:137]
	s_add_u32 s2, s2, s0
	s_mov_b32 m0, s45
	s_addc_u32 s3, s3, s1
	global_load_lds_dwordx4 v[234:235], off
	v_lshl_add_u64 v[236:237], s[2:3], 0, v[136:137]
	s_mov_b32 m0, s46
	s_nop 0
	global_load_lds_dwordx4 v[236:237], off
	s_waitcnt vmcnt(6)
	s_barrier
	v_mfma_f32_16x16x32_bf16 v[48:51], v[212:215], v[180:183], v[48:51]
	v_mfma_f32_16x16x32_bf16 v[44:47], v[220:223], v[180:183], v[44:47]
	v_mfma_f32_16x16x32_bf16 v[32:35], v[212:215], v[188:191], v[32:35]
	v_mfma_f32_16x16x32_bf16 v[28:31], v[220:223], v[188:191], v[28:31]
	v_mfma_f32_16x16x32_bf16 v[16:19], v[212:215], v[196:199], v[16:19]
	v_mfma_f32_16x16x32_bf16 v[12:15], v[220:223], v[196:199], v[12:15]
	v_mfma_f32_16x16x32_bf16 v[8:11], v[212:215], v[204:207], v[8:11]
	v_mfma_f32_16x16x32_bf16 v[4:7], v[220:223], v[204:207], v[4:7]
	v_mfma_f32_16x16x32_bf16 v[48:51], v[216:219], v[184:187], v[48:51]
	v_mfma_f32_16x16x32_bf16 v[44:47], v[224:227], v[184:187], v[44:47]
	v_mfma_f32_16x16x32_bf16 v[32:35], v[216:219], v[192:195], v[32:35]
	v_mfma_f32_16x16x32_bf16 v[28:31], v[224:227], v[192:195], v[28:31]
	v_mfma_f32_16x16x32_bf16 v[16:19], v[216:219], v[200:203], v[16:19]
	v_mfma_f32_16x16x32_bf16 v[12:15], v[224:227], v[200:203], v[12:15]
	v_mfma_f32_16x16x32_bf16 v[8:11], v[216:219], v[208:211], v[8:11]
	v_mfma_f32_16x16x32_bf16 v[4:7], v[224:227], v[208:211], v[4:7]
	s_barrier
	ds_read_b128 v[164:167], v162
	ds_read_b128 v[168:171], v162 offset:1024
	ds_read_b128 v[172:175], v162 offset:2048
	ds_read_b128 v[176:179], v162 offset:3072
	s_add_u32 s2, s72, s70
	s_addc_u32 s3, s73, s71
	v_lshl_add_u64 v[212:213], s[2:3], 0, v[232:233]
	s_add_u32 s2, s2, s70
	s_mov_b32 m0, s47
	s_addc_u32 s3, s3, s71
	ds_read_b128 v[180:183], v144 offset:32768
	ds_read_b128 v[184:187], v144 offset:33792
	ds_read_b128 v[188:191], v145 offset:32768
	ds_read_b128 v[192:195], v145 offset:33792
	ds_read_b128 v[196:199], v159 offset:32768
	ds_read_b128 v[200:203], v159 offset:33792
	ds_read_b128 v[204:207], v160 offset:32768
	ds_read_b128 v[208:211], v160 offset:33792
	global_load_lds_dwordx4 v[212:213], off
	v_lshl_add_u64 v[212:213], s[2:3], 0, v[232:233]
	s_mov_b32 m0, s48
	s_nop 0
	global_load_lds_dwordx4 v[212:213], off
	s_waitcnt lgkmcnt(8)
	s_barrier
	s_waitcnt lgkmcnt(0)
	v_mfma_f32_16x16x32_bf16 v[128:131], v[164:167], v[180:183], v[128:131]
	v_mfma_f32_16x16x32_bf16 v[124:127], v[172:175], v[180:183], v[124:127]
	v_mfma_f32_16x16x32_bf16 v[120:123], v[164:167], v[188:191], v[120:123]
	v_mfma_f32_16x16x32_bf16 v[116:119], v[172:175], v[188:191], v[116:119]
	v_mfma_f32_16x16x32_bf16 v[104:107], v[164:167], v[196:199], v[104:107]
	v_mfma_f32_16x16x32_bf16 v[100:103], v[172:175], v[196:199], v[100:103]
	v_mfma_f32_16x16x32_bf16 v[88:91], v[164:167], v[204:207], v[88:91]
	v_mfma_f32_16x16x32_bf16 v[84:87], v[172:175], v[204:207], v[84:87]
	v_mfma_f32_16x16x32_bf16 v[128:131], v[168:171], v[184:187], v[128:131]
	v_mfma_f32_16x16x32_bf16 v[124:127], v[176:179], v[184:187], v[124:127]
	v_mfma_f32_16x16x32_bf16 v[120:123], v[168:171], v[192:195], v[120:123]
	v_mfma_f32_16x16x32_bf16 v[116:119], v[176:179], v[192:195], v[116:119]
	v_mfma_f32_16x16x32_bf16 v[104:107], v[168:171], v[200:203], v[104:107]
	v_mfma_f32_16x16x32_bf16 v[100:103], v[176:179], v[200:203], v[100:103]
	v_mfma_f32_16x16x32_bf16 v[88:91], v[168:171], v[208:211], v[88:91]
	v_mfma_f32_16x16x32_bf16 v[84:87], v[176:179], v[208:211], v[84:87]
	s_barrier
	v_lshl_add_u64 v[228:229], v[228:229], 0, s[22:23]
	s_add_i32 m0, s42, 0x18000
	ds_read_b128 v[212:215], v163
	ds_read_b128 v[216:219], v163 offset:1024
	ds_read_b128 v[220:223], v163 offset:2048
	ds_read_b128 v[224:227], v163 offset:3072
	global_load_lds_dwordx4 v[228:229], off
	v_lshl_add_u64 v[228:229], v[230:231], 0, s[22:23]
	s_add_i32 m0, s42, 0x1a000
	s_nop 0
	global_load_lds_dwordx4 v[228:229], off
	s_barrier
; #define LDA(dst, b, h) for (int m = 0; m < 4; ++m) for (int k = 0; k < 2; ++k) \
;     dst[m][k] = *reinterpret_cast<const bf16x8*>(SA(b, h) + lds_byte(wr * 64 + m * 16 + fr, k * 32 + fq * 8))
; #define LDB(dst, b, h) for (int n = 0; n < 2; ++n) for (int k = 0; k < 2; ++k) \
;     dst[n][k] = *reinterpret_cast<const bf16x8*>(SB(b, h) + lds_byte(wc * 32 + n * 16 + fr, k * 32 + fq * 8))
; #define MMA(ai, bj, At_, Bt_) do { __builtin_amdgcn_s_setprio(1); \
;     for (int m = 0; m < 4; ++m) for (int n = 0; n < 2; ++n) for (int k = 0; k < 2; ++k) \
;       acc[ai][bj][m][n] = __builtin_amdgcn_mfma_f32_16x16x32_bf16(Bt_[n][k], At_[m][k], acc[ai][bj][m][n], 0, 0, 0); \
;     __builtin_amdgcn_s_setprio(0); } while (0)
; #define WAIT_V(n) asm volatile("s_waitcnt vmcnt(" #n ")" ::: "memory")
; #define WAIT_L(n) asm volatile("s_waitcnt lgkmcnt(" #n ")" ::: "memory")
; #define BAR __builtin_amdgcn_s_barrier()
; #define SCHED __builtin_amdgcn_sched_barrier(0)
; #define STG(P, PTR, LD, O0) do { const bf16_t* _g = (PTR); \
;     __builtin_amdgcn_global_load_lds((const unsigned*)(_g + O0), (lds_u32*)((P) + swave * 1024), 16, 0, 0); \
;     __builtin_amdgcn_global_load_lds((const unsigned*)(_g + (size_t)64 * (LD) + O0), (lds_u32*)((P) + swave * 1024 + 8192), 16, 0, 0); } while (0)
; #define LDA(dst, b, h) for (int m = 0; m < 4; ++m) for (int k = 0; k < 2; ++k) \
;     dst[m][k] = *reinterpret_cast<const bf16x8*>(SA(b, h) + lds_byte(wr * 64 + m * 16 + fr, k * 32 + fq * 8))
; #define LDB(dst, b, h) for (int n = 0; n < 2; ++n) for (int k = 0; k < 2; ++k) \
;     dst[n][k] = *reinterpret_cast<const bf16x8*>(SB(b, h) + lds_byte(wc * 32 + n * 16 + fr, k * 32 + fq * 8))
; #define WAIT_V(n) asm volatile("s_waitcnt vmcnt(" #n ")" ::: "memory")
; #define WAIT_L(n) asm volatile("s_waitcnt lgkmcnt(" #n ")" ::: "memory")
; #define BAR __builtin_amdgcn_s_barrier()
; #define SCHED __builtin_amdgcn_sched_barrier(0)
; __device__ __forceinline__ void gemm_stream(int swave, const GemmJob& J, char* shm, int vb, int G) {
;     ...
;       WAIT_L(8); BAR; WAIT_L(0); MMA(0, 0, At, B0); BAR; SCHED;
;       LDB(B1, 1, 1); STG(SB(1, 0), b3, ldb, offB0);
;       BAR; WAIT_L(0); MMA(0, 1, At, B1); BAR;
;       LDA(At, 1, 1); STGA(SA(1, 0), xA, xA1, k2 + 1, 0);
;       BAR; WAIT_L(0); MMA(1, 0, At, B0); BAR; SCHED;
;       STG(SB(1, 1), b3 + hB, ldb, offB0);
;       WAIT_V(6); BAR; MMA(1, 1, At, B1); BAR;
	s_waitcnt lgkmcnt(0)
	v_mfma_f32_16x16x32_bf16 v[112:115], v[212:215], v[180:183], v[112:115]
	v_mfma_f32_16x16x32_bf16 v[108:111], v[220:223], v[180:183], v[108:111]
	s_or_b32 s68, s68, 1
	s_cmp_lt_u32 s68, s36
	v_mfma_f32_16x16x32_bf16 v[96:99], v[212:215], v[188:191], v[96:99]
	s_cselect_b64 vcc, -1, 0
	s_and_b64 s[2:3], vcc, exec
	v_mfma_f32_16x16x32_bf16 v[92:95], v[220:223], v[188:191], v[92:95]
	s_cselect_b32 s69, s38, s37
	s_sub_i32 s2, s68, s36
	v_mfma_f32_16x16x32_bf16 v[80:83], v[212:215], v[196:199], v[80:83]
	s_min_u32 s94, s68, s2
	s_and_b64 s[2:3], vcc, exec
	v_mfma_f32_16x16x32_bf16 v[76:79], v[220:223], v[196:199], v[76:79]
	s_cselect_b32 s64, s64, s66
	s_cselect_b32 s52, s52, s65
	v_mfma_f32_16x16x32_bf16 v[72:75], v[212:215], v[204:207], v[72:75]
	s_lshl_b64 s[2:3], s[94:95], 7
	v_cndmask_b32_e32 v2, v138, v0, vcc
	v_mfma_f32_16x16x32_bf16 v[68:71], v[220:223], v[204:207], v[68:71]
	s_add_u32 s2, s52, s2
	v_mfma_f32_16x16x32_bf16 v[112:115], v[216:219], v[184:187], v[112:115]
	s_addc_u32 s3, s64, s3
	v_mfma_f32_16x16x32_bf16 v[108:111], v[224:227], v[184:187], v[108:111]
	v_lshlrev_b64 v[228:229], 1, v[2:3]
	v_mfma_f32_16x16x32_bf16 v[96:99], v[216:219], v[192:195], v[96:99]
	s_lshl_b32 s52, s69, 7
	v_mfma_f32_16x16x32_bf16 v[92:95], v[224:227], v[192:195], v[92:95]
	v_lshl_add_u64 v[230:231], s[2:3], 0, v[228:229]
	v_mfma_f32_16x16x32_bf16 v[80:83], v[216:219], v[200:203], v[80:83]
	s_add_u32 s2, s2, s52
	v_mfma_f32_16x16x32_bf16 v[76:79], v[224:227], v[200:203], v[76:79]
	s_mov_b32 m0, s54
	v_mfma_f32_16x16x32_bf16 v[72:75], v[216:219], v[208:211], v[72:75]
	s_addc_u32 s3, s3, 0
	v_mfma_f32_16x16x32_bf16 v[68:71], v[224:227], v[208:211], v[68:71]
	s_barrier
	ds_read_b128 v[180:183], v144 offset:49152
	ds_read_b128 v[184:187], v144 offset:50176
	ds_read_b128 v[188:191], v145 offset:49152
	ds_read_b128 v[192:195], v145 offset:50176
	ds_read_b128 v[196:199], v159 offset:49152
	ds_read_b128 v[200:203], v159 offset:50176
	ds_read_b128 v[204:207], v160 offset:49152
	ds_read_b128 v[208:211], v160 offset:50176
	global_load_lds_dwordx4 v[230:231], off
	v_lshl_add_u64 v[228:229], s[2:3], 0, v[228:229]
	s_mov_b32 m0, s55
	s_nop 0
	global_load_lds_dwordx4 v[228:229], off
	s_barrier
	s_waitcnt lgkmcnt(0)
	v_mfma_f32_16x16x32_bf16 v[64:67], v[164:167], v[180:183], v[64:67]
	v_mfma_f32_16x16x32_bf16 v[60:63], v[172:175], v[180:183], v[60:63]
	v_mfma_f32_16x16x32_bf16 v[56:59], v[164:167], v[188:191], v[56:59]
	v_mfma_f32_16x16x32_bf16 v[52:55], v[172:175], v[188:191], v[52:55]
	v_mfma_f32_16x16x32_bf16 v[40:43], v[164:167], v[196:199], v[40:43]
	v_mfma_f32_16x16x32_bf16 v[36:39], v[172:175], v[196:199], v[36:39]
	v_mfma_f32_16x16x32_bf16 v[24:27], v[164:167], v[204:207], v[24:27]
	v_mfma_f32_16x16x32_bf16 v[20:23], v[172:175], v[204:207], v[20:23]
	v_mfma_f32_16x16x32_bf16 v[64:67], v[168:171], v[184:187], v[64:67]
	v_mfma_f32_16x16x32_bf16 v[60:63], v[176:179], v[184:187], v[60:63]
	v_mfma_f32_16x16x32_bf16 v[56:59], v[168:171], v[192:195], v[56:59]
	v_mfma_f32_16x16x32_bf16 v[52:55], v[176:179], v[192:195], v[52:55]
	v_mfma_f32_16x16x32_bf16 v[40:43], v[168:171], v[200:203], v[40:43]
	v_mfma_f32_16x16x32_bf16 v[36:39], v[176:179], v[200:203], v[36:39]
	v_mfma_f32_16x16x32_bf16 v[24:27], v[168:171], v[208:211], v[24:27]
	v_mfma_f32_16x16x32_bf16 v[20:23], v[176:179], v[208:211], v[20:23]
	s_barrier
	v_lshl_add_u64 v[164:165], v[234:235], 0, s[22:23]
	s_add_i32 m0, s42, 0x1c000
	s_nop 0
	global_load_lds_dwordx4 v[164:165], off
	v_lshl_add_u64 v[164:165], v[236:237], 0, s[22:23]
	s_add_i32 m0, s42, 0x1e000
	s_nop 0
	global_load_lds_dwordx4 v[164:165], off
	s_waitcnt vmcnt(6)
	s_barrier
	v_mfma_f32_16x16x32_bf16 v[48:51], v[212:215], v[180:183], v[48:51]
	v_mfma_f32_16x16x32_bf16 v[44:47], v[220:223], v[180:183], v[44:47]
	s_add_i32 s29, s29, 2
	v_mfma_f32_16x16x32_bf16 v[32:35], v[212:215], v[188:191], v[32:35]
	s_add_u32 s20, s20, 0x100
	v_mfma_f32_16x16x32_bf16 v[28:31], v[220:223], v[188:191], v[28:31]
	s_addc_u32 s21, s21, 0
	v_mfma_f32_16x16x32_bf16 v[16:19], v[212:215], v[196:199], v[16:19]
	s_cmp_ge_u32 s33, s49
	v_mfma_f32_16x16x32_bf16 v[12:15], v[220:223], v[196:199], v[12:15]
	s_mov_b32 s2, s33
	v_mfma_f32_16x16x32_bf16 v[8:11], v[212:215], v[204:207], v[8:11]
	v_mfma_f32_16x16x32_bf16 v[4:7], v[220:223], v[204:207], v[4:7]
	v_mfma_f32_16x16x32_bf16 v[48:51], v[216:219], v[184:187], v[48:51]
	v_mfma_f32_16x16x32_bf16 v[44:47], v[224:227], v[184:187], v[44:47]
	v_mfma_f32_16x16x32_bf16 v[32:35], v[216:219], v[192:195], v[32:35]
	v_mfma_f32_16x16x32_bf16 v[28:31], v[224:227], v[192:195], v[28:31]
	v_mfma_f32_16x16x32_bf16 v[16:19], v[216:219], v[200:203], v[16:19]
	v_mfma_f32_16x16x32_bf16 v[12:15], v[224:227], v[200:203], v[12:15]
	v_mfma_f32_16x16x32_bf16 v[8:11], v[216:219], v[208:211], v[8:11]
	v_mfma_f32_16x16x32_bf16 v[4:7], v[224:227], v[208:211], v[4:7]
	s_barrier
; __device__ __forceinline__ unsigned pk2(float lo, float hi) { f32x2_t v = {lo, hi}; bf16x2_t b = __builtin_convertvector(v, bf16x2_t); return __builtin_bit_cast(unsigned, b); }
; __device__ __forceinline__ void gemm_stream(int swave, const GemmJob& J, char* shm, int vb, int G) {
;     ...
;       bf16_t* C = (bf16_t*)((char*)J.c0 + (size_t)cg * J.strideC);
; #pragma unroll
;       for (int ai = 0; ai < 2; ++ai)
; #pragma unroll
;         for (int m = 0; m < 4; ++m)
; #pragma unroll
;           for (int bj = 0; bj < 2; ++bj) {
;             const f32x4 v0 = acc[ai][bj][m][0], v1 = acc[ai][bj][m][1];
;             uint4 o; o.x = pk2(v0[0], v0[1]); o.y = pk2(v0[2], v0[3]); o.z = pk2(v1[0], v1[1]); o.w = pk2(v1[2], v1[3]);
;             *(uint4*)(C + (size_t)(cbrow + ai * 128 + wr * 64 + m * 16 + fr) * J.ldc + cbcol + bj * 128 + wc * 32 + fq * 8) = o;
;           }
;     }
;     if (!has_next) break;
	s_cbranch_scc0 .LBB0_729
	v_add_u32_e32 v164, s5, v1
	s_ashr_i32 s5, s4, 31
	s_lshl_b64 s[2:3], s[4:5], 1
	v_ashrrev_i32_e32 v2, 31, v164
	s_add_u32 s2, s50, s2
	v_cvt_pk_bf16_f32 v128, v128, v129
	v_cvt_pk_bf16_f32 v129, v130, v131
	v_cvt_pk_bf16_f32 v130, v124, v125
	v_mul_lo_u32 v2, v2, s18
	v_mad_u64_u32 v[124:125], s[4:5], v164, s18, 0
	s_addc_u32 s3, s51, s3
	v_add_u32_e32 v125, v125, v2
	v_lshl_add_u64 v[124:125], v[124:125], 1, s[2:3]
	v_mov_b32_e32 v141, v3
	v_lshl_add_u64 v[124:125], v[124:125], 0, v[140:141]
	v_mov_b32_e32 v143, v3
	v_lshl_add_u64 v[124:125], v[124:125], 0, v[142:143]
	s_lshl_b32 s2, s18, 5
	s_mov_b32 s3, 0
	s_mul_i32 s4, s18, 0xa0
	s_mov_b32 s5, 0
	v_cvt_pk_bf16_f32 v112, v112, v113
	v_cvt_pk_bf16_f32 v113, v114, v115
	v_cvt_pk_bf16_f32 v114, v108, v109
	v_cvt_pk_bf16_f32 v115, v110, v111
	global_store_dwordx4 v[124:125], v[112:115], off offset:256
	v_cvt_pk_bf16_f32 v131, v126, v127
	v_cvt_pk_bf16_f32 v96, v96, v97
	v_lshl_add_u64 v[112:113], v[124:125], 0, s[2:3]
	v_cvt_pk_bf16_f32 v97, v98, v99
	v_cvt_pk_bf16_f32 v98, v92, v93
	v_cvt_pk_bf16_f32 v99, v94, v95
	global_store_dwordx4 v[124:125], v[128:131], off
	global_store_dwordx4 v[112:113], v[96:99], off offset:256
	v_cvt_pk_bf16_f32 v108, v120, v121
	v_cvt_pk_bf16_f32 v109, v122, v123
	v_lshl_add_u64 v[96:97], v[112:113], 0, s[2:3]
	v_cvt_pk_bf16_f32 v110, v116, v117
	v_cvt_pk_bf16_f32 v111, v118, v119
	v_cvt_pk_bf16_f32 v80, v80, v81
	v_cvt_pk_bf16_f32 v81, v82, v83
	v_cvt_pk_bf16_f32 v82, v76, v77
	v_cvt_pk_bf16_f32 v83, v78, v79
	global_store_dwordx4 v[112:113], v[108:111], off
	global_store_dwordx4 v[96:97], v[80:83], off offset:256
	v_cvt_pk_bf16_f32 v64, v64, v65
	v_cvt_pk_bf16_f32 v65, v66, v67
	v_lshl_add_u64 v[80:81], v[96:97], 0, s[2:3]
	v_cvt_pk_bf16_f32 v66, v60, v61
	v_lshl_add_u64 v[60:61], v[80:81], 0, s[4:5]
	v_cvt_pk_bf16_f32 v72, v72, v73
	v_cvt_pk_bf16_f32 v73, v74, v75
	v_cvt_pk_bf16_f32 v74, v68, v69
	v_cvt_pk_bf16_f32 v67, v62, v63
	v_cvt_pk_bf16_f32 v92, v104, v105
	v_cvt_pk_bf16_f32 v93, v106, v107
	v_cvt_pk_bf16_f32 v94, v100, v101
	v_cvt_pk_bf16_f32 v95, v102, v103
	v_cvt_pk_bf16_f32 v76, v88, v89
	v_cvt_pk_bf16_f32 v77, v90, v91
	v_cvt_pk_bf16_f32 v78, v84, v85
	v_cvt_pk_bf16_f32 v79, v86, v87
	v_cvt_pk_bf16_f32 v75, v70, v71
	v_cvt_pk_bf16_f32 v48, v48, v49
	v_cvt_pk_bf16_f32 v49, v50, v51
	v_cvt_pk_bf16_f32 v50, v44, v45
	v_cvt_pk_bf16_f32 v51, v46, v47
	global_store_dwordx4 v[96:97], v[92:95], off
	global_store_dwordx4 v[80:81], v[76:79], off
	global_store_dwordx4 v[80:81], v[72:75], off offset:256
	global_store_dwordx4 v[60:61], v[48:51], off offset:256
	v_cvt_pk_bf16_f32 v32, v32, v33
	v_cvt_pk_bf16_f32 v33, v34, v35
	v_lshl_add_u64 v[48:49], v[60:61], 0, s[2:3]
	v_cvt_pk_bf16_f32 v34, v28, v29
	v_cvt_pk_bf16_f32 v35, v30, v31
	global_store_dwordx4 v[60:61], v[64:67], off
	global_store_dwordx4 v[48:49], v[32:35], off offset:256
	v_cvt_pk_bf16_f32 v44, v56, v57
	v_cvt_pk_bf16_f32 v45, v58, v59
	v_lshl_add_u64 v[32:33], v[48:49], 0, s[2:3]
	v_cvt_pk_bf16_f32 v46, v52, v53
	v_cvt_pk_bf16_f32 v47, v54, v55
	v_cvt_pk_bf16_f32 v16, v16, v17
	v_cvt_pk_bf16_f32 v17, v18, v19
	v_cvt_pk_bf16_f32 v18, v12, v13
	v_cvt_pk_bf16_f32 v19, v14, v15
	global_store_dwordx4 v[48:49], v[44:47], off
	global_store_dwordx4 v[32:33], v[16:19], off offset:256
	v_cvt_pk_bf16_f32 v28, v40, v41
	v_cvt_pk_bf16_f32 v29, v42, v43
	v_lshl_add_u64 v[16:17], v[32:33], 0, s[2:3]
	v_cvt_pk_bf16_f32 v30, v36, v37
	v_cvt_pk_bf16_f32 v31, v38, v39
	v_cvt_pk_bf16_f32 v12, v24, v25
	v_cvt_pk_bf16_f32 v13, v26, v27
	v_cvt_pk_bf16_f32 v14, v20, v21
	v_cvt_pk_bf16_f32 v15, v22, v23
	v_cvt_pk_bf16_f32 v8, v8, v9
	v_cvt_pk_bf16_f32 v9, v10, v11
	v_cvt_pk_bf16_f32 v10, v4, v5
	v_cvt_pk_bf16_f32 v11, v6, v7
	s_and_b64 vcc, exec, s[6:7]
	s_mov_b64 s[2:3], s[14:15]
	s_mov_b64 s[16:17], s[12:13]
	s_mov_b64 s[8:9], s[10:11]
	s_mov_b32 s4, s56
	s_mov_b32 s5, s28
	global_store_dwordx4 v[32:33], v[28:31], off
	global_store_dwordx4 v[16:17], v[12:15], off
	global_store_dwordx4 v[16:17], v[8:11], off offset:256
	s_cbranch_vccz .LBB0_726
	s_waitcnt vmcnt(0)
	s_movk_i32 s66, 0x100
	v_cmp_gt_u32_e32 vcc, s66, v135
	s_and_saveexec_b64 s[0:1], vcc
	s_cbranch_execz .LBB0_733
	s_barrier
